# speedup vs baseline: 1.0057x; 1.0057x over previous
; DI unsigned xb_ld(unsigned* p)              { return __hip_atomic_load(p, __ATOMIC_RELAXED, __HIP_MEMORY_SCOPE_AGENT); }
; DI unsigned xb_add(unsigned* p, unsigned v) { return __hip_atomic_fetch_add(p, v, __ATOMIC_RELAXED, __HIP_MEMORY_SCOPE_AGENT); }
; #define XB_SPIN(cond, bar) do { unsigned _sp = 0; while (cond) { __builtin_amdgcn_s_sleep(1); \
;     if ((++_sp & 255u) == 0u) { if (xb_ld(&(bar)[XB_TMO])) break; if (_sp > XB_SPIN_CAP) { atomicAdd(&(bar)[XB_TMO], 1u); break; } } } } while (0)
; DI void xcd_barrier(const XcdBarrier& b) {
;     ...
;     const unsigned old = xb_add(&bar[XB_XSUB(b.x)], 1u);
;     const unsigned gen = old / nloc;
;     if (old + 1u == (gen + 1u) * nloc) {
;     ...
;     } else {
;       XB_SPIN(xb_ld(&bar[XB_XGEN(b.x)]) == gen, bar);
.LBB0_377:
	s_or_b64 exec, exec, s[6:7]
	v_cvt_f32_u32_e32 v4, v2
	s_waitcnt vmcnt(0)
	v_readfirstlane_b32 s2, v3
	v_sub_u32_e32 v3, 0, v2
	v_rcp_iflag_f32_e32 v4, v4
	v_add_u32_e32 v5, s2, v1
	v_mul_f32_e32 v4, 0x4f7ffffe, v4
	v_cvt_u32_f32_e32 v4, v4
	v_mul_lo_u32 v1, v3, v4
	v_mul_hi_u32 v1, v4, v1
	v_add_u32_e32 v1, v4, v1
	v_mul_hi_u32 v1, v5, v1
	v_mul_lo_u32 v3, v1, v2
	v_sub_u32_e32 v3, v5, v3
	v_add_u32_e32 v4, 1, v1
	v_cmp_ge_u32_e32 vcc, v3, v2
	s_nop 1
	v_cndmask_b32_e32 v1, v1, v4, vcc
	v_sub_u32_e32 v4, v3, v2
	v_cndmask_b32_e32 v3, v3, v4, vcc
	v_add_u32_e32 v4, 1, v1
	v_cmp_ge_u32_e32 vcc, v3, v2
	v_add_u32_e32 v3, 1, v5
	s_nop 0
	v_cndmask_b32_e32 v1, v1, v4, vcc
	v_mul_lo_u32 v4, v2, v1
	v_add_u32_e32 v2, v4, v2
	v_cmp_ne_u32_e32 vcc, v3, v2
	s_and_saveexec_b64 s[6:7], vcc
	s_xor_b64 s[12:13], exec, s[6:7]
	s_cbranch_execz .LBB0_391
	v_readlane_b32 s6, v254, 17
	v_readlane_b32 s7, v254, 18
	s_waitcnt lgkmcnt(0)
	s_nop 3
	global_load_dword v0, v97, s[6:7] sc1
	s_waitcnt vmcnt(0)
	v_cmp_eq_u32_e32 vcc, v0, v1
	s_and_saveexec_b64 s[14:15], vcc
	s_cbranch_execz .LBB0_390
	s_mov_b32 s6, 1
	s_mov_b64 s[36:37], 0
	s_branch .LBB0_381

.LBB0_385:
	v_readlane_b32 s40, v254, 17
	v_readlane_b32 s41, v254, 18
	s_add_i32 s6, s6, 1
	s_mov_b64 s[42:43], -1
	s_nop 2
	global_load_dword v0, v97, s[40:41] sc1
	s_waitcnt vmcnt(0)
	v_cmp_ne_u32_e32 vcc, v0, v1
	s_orn2_b64 s[40:41], vcc, exec
	s_branch .LBB0_380

; DI unsigned xb_add(unsigned* p, unsigned v) { return __hip_atomic_fetch_add(p, v, __ATOMIC_RELAXED, __HIP_MEMORY_SCOPE_AGENT); }
; DI void xcd_barrier(const XcdBarrier& b) {
;     ...
;       __builtin_amdgcn_fence(__ATOMIC_ACQUIRE, "agent");
;       xb_add(&bar[XB_XGEN(b.x)], 1u);
;       asm volatile("s_waitcnt vmcnt(0)" ::: "memory");
.LBB0_409:
	s_or_b64 exec, exec, s[6:7]
	s_mov_b64 s[6:7], exec
	v_mbcnt_lo_u32_b32 v0, s6, 0
	v_mbcnt_hi_u32_b32 v0, s7, v0
	v_cmp_eq_u32_e32 vcc, 0, v0
	s_waitcnt vmcnt(0)
	buffer_inv sc1
	s_and_saveexec_b64 s[12:13], vcc
	s_cbranch_execz .LBB0_21
	s_bcnt1_i32_b64 s2, s[6:7]
	v_readlane_b32 s6, v254, 13
	v_mov_b32_e32 v0, s2
	v_readlane_b32 s7, v254, 14
	s_nop 4
	s_branch .LBB0_21
